# steps 10/12 start at block 128 (run beside 9/11), first grid barrier through the XCD barrier, no store drain before next-unit row-sum loads in EVIN/ODIN
# speedup vs baseline: 1.0741x; 1.0080x over previous
; #define LAS __attribute__((address_space(3)))
; __global__ void __launch_bounds__(512) fwd_kernel(Params p) {
;     ...
;         t[0] = (unsigned)fl; put64(t, 2, (unsigned long long)g.A0); put64(t, 4, (unsigned long long)g.B0); t[6] = g.lda; t[7] = g.ldb; t[8] = g.K; t[9] = g.nM; t[10] = g.nN; t[11] = g.nz; t[12] = g.nz2;
;         put64(t, 14, (unsigned long long)g.sA1); put64(t, 16, (unsigned long long)g.sA2); put64(t, 18, (unsigned long long)g.sB1); put64(t, 20, (unsigned long long)g.sB2); t[22] = g.mode; t[23] = g.c0;
;         put64(t, 24, (unsigned long long)g.o0); put64(t, 26, (unsigned long long)g.o1); put64(t, 28, (unsigned long long)g.o2); put64(t, 30, (unsigned long long)g.o3); put64(t, 32, (unsigned long long)g.o4);
;         put64(t, 34, (unsigned long long)g.f0); put64(t, 36, (unsigned long long)g.f1); t[38] = g.ldc; t[39] = g.ro1; t[40] = g.co2; t[41] = __float_as_uint(g.scale); t[42] = g.ro2; put64(t, 44, (unsigned long long)g.f2); t[46] = g.kstA; t[47] = g.kstB; put64(t, 48, (unsigned long long)g.pstA); put64(t, 50, (unsigned long long)g.pstB);
;     }
;     if (threadIdx.x < 4) ((LAS unsigned*)(lds + LDS_BARST))[threadIdx.x] = 0u;
.LBB0_64:
	s_or_b64 exec, exec, s[0:1]
	v_cmp_gt_u32_e32 vcc, 4, v201
	s_and_saveexec_b64 s[0:1], vcc
	v_lshl_add_u32 v1, v201, 2, 0
	v_add_u32_e32 v1, 0x23000, v1
	v_mov_b32_e32 v2, 0
	ds_write_b32 v1, v2
	v_mov_b32_e32 v2, 0x80
	v_mov_b32_e32 v1, 0x21a5c
	ds_write_b32 v1, v2
	ds_write_b32 v1, v2 offset:512
	s_or_b64 exec, exec, s[0:1]
	s_waitcnt lgkmcnt(0)
	s_barrier
	s_getreg_b32 s4, hwreg(HW_REG_XCC_ID, 0, 4)
	s_mov_b32 s39, 0
	v_cmp_eq_u32_e32 vcc, 0, v201
	s_and_saveexec_b64 s[0:1], vcc
	s_cbranch_execz .LBB0_69
	s_mov_b64 s[2:3], exec
	v_mbcnt_lo_u32_b32 v1, s2, 0
	v_mbcnt_hi_u32_b32 v1, s3, v1
	v_cmp_eq_u32_e32 vcc, 0, v1
	s_and_b64 s[6:7], exec, vcc
	s_mov_b64 exec, s[6:7]
	s_cbranch_execz .LBB0_69
	s_lshl_b32 s4, s4, 8
	s_and_b32 s4, s4, 0xf00
	s_add_u32 s4, s10, s4
	s_addc_u32 s5, s11, 0
	s_bcnt1_i32_b64 s2, s[2:3]
	v_mov_b32_e32 v1, 0x10000
	v_mov_b32_e32 v2, s2
	global_atomic_add v1, v2, s[4:5] offset:1024

; __device__ __forceinline__ void rsv_load(float (&rsv)[2][4], const GD& g, const pg8::Unit& u, int wr, int fr) {
;     if (g.f2) { const int rg = (u.z / g.nz2) * g.ro1 + u.pm * 256 + wr * 64 + fr;
; #pragma unroll
;         for (int ai = 0; ai < 2; ++ai)
; #pragma unroll
;             for (int m = 0; m < 4; ++m) rsv[ai][m] = g.f2[rg + ai * 128 + m * 16]; }
.LBB0_346:
	s_and_b64 vcc, exec, s[6:7]
	s_cbranch_vccnz .LBB0_348
	s_ashr_i32 s0, s4, 31
	v_readlane_b32 s1, v255, 2
	s_xor_b32 s0, s0, s1
	s_abs_i32 s1, s4
	v_readlane_b32 s2, v255, 6
	s_mul_hi_u32 s2, s1, s2
	s_mul_i32 s3, s2, s79
	s_sub_i32 s1, s1, s3
	s_add_i32 s3, s2, 1
	s_sub_i32 s6, s1, s79
	s_cmp_ge_u32 s1, s79
	s_cselect_b32 s2, s3, s2
	s_cselect_b32 s1, s6, s1
	s_add_i32 s3, s2, 1
	s_cmp_ge_u32 s1, s79
	s_cselect_b32 s1, s3, s2
	s_xor_b32 s1, s1, s0
	s_sub_i32 s0, s1, s0
	v_readlane_b32 s1, v254, 59
	s_mul_i32 s0, s0, s1
	s_lshl_b32 s1, s76, 8
	s_add_i32 s0, s0, s1
	v_add_u32_e32 v2, s0, v163
	v_readlane_b32 s0, v254, 52
	v_ashrrev_i32_e32 v3, 31, v2
	v_readlane_b32 s1, v254, 53
	s_nop 1
	v_lshl_add_u64 v[2:3], v[2:3], 2, s[0:1]
	flat_load_dword v164, v[2:3]
	flat_load_dword v165, v[2:3] offset:64
	flat_load_dword v166, v[2:3] offset:128
	flat_load_dword v167, v[2:3] offset:192
	flat_load_dword v168, v[2:3] offset:512
	flat_load_dword v169, v[2:3] offset:576
	flat_load_dword v170, v[2:3] offset:640
	flat_load_dword v171, v[2:3] offset:704

; __device__ __forceinline__ void rsv_load(float (&rsv)[2][4], const GD& g, const pg8::Unit& u, int wr, int fr) {
;     if (g.f2) { const int rg = (u.z / g.nz2) * g.ro1 + u.pm * 256 + wr * 64 + fr;
; #pragma unroll
;         for (int ai = 0; ai < 2; ++ai)
; #pragma unroll
;             for (int m = 0; m < 4; ++m) rsv[ai][m] = g.f2[rg + ai * 128 + m * 16]; }
.LBB0_479:
	s_and_b64 vcc, exec, s[6:7]
	s_cbranch_vccnz .LBB0_481
	s_ashr_i32 s0, s31, 31
	v_readlane_b32 s1, v254, 63
	s_xor_b32 s0, s0, s1
	s_abs_i32 s1, s31
	v_readlane_b32 s2, v255, 2
	s_mul_hi_u32 s2, s1, s2
	s_mul_i32 s3, s2, s30
	s_sub_i32 s1, s1, s3
	s_add_i32 s3, s2, 1
	s_sub_i32 s6, s1, s30
	s_cmp_ge_u32 s1, s30
	s_cselect_b32 s2, s3, s2
	s_cselect_b32 s1, s6, s1
	s_add_i32 s3, s2, 1
	s_cmp_ge_u32 s1, s30
	s_cselect_b32 s1, s3, s2
	s_xor_b32 s1, s1, s0
	s_sub_i32 s0, s1, s0
	v_readlane_b32 s1, v254, 59
	s_mul_i32 s0, s0, s1
	s_lshl_b32 s1, s92, 8
	s_add_i32 s0, s0, s1
	v_add_u32_e32 v2, s0, v164
	v_readlane_b32 s0, v254, 52
	v_ashrrev_i32_e32 v3, 31, v2
	v_readlane_b32 s1, v254, 53
	s_nop 1
	v_lshl_add_u64 v[2:3], v[2:3], 2, s[0:1]
	flat_load_dword v165, v[2:3]
	flat_load_dword v166, v[2:3] offset:64
	flat_load_dword v167, v[2:3] offset:128
	flat_load_dword v168, v[2:3] offset:192
	flat_load_dword v169, v[2:3] offset:512
	flat_load_dword v170, v[2:3] offset:576
	flat_load_dword v171, v[2:3] offset:640
	flat_load_dword v172, v[2:3] offset:704

; #define LAS __attribute__((address_space(3)))
; __device__ __forceinline__ unsigned xb_add(unsigned* p, unsigned v) { return __hip_atomic_fetch_add(p, v, __ATOMIC_RELAXED, __HIP_MEMORY_SCOPE_AGENT); }
; __device__ __forceinline__ unsigned xb_xcc_id() { return (unsigned)__builtin_amdgcn_s_getreg((3 << 11) | 20) & 0xFu; }
; __device__ __forceinline__ void xcd_barrier(const XcdBarrier& b, const int tid0) {
;     asm volatile("s_waitcnt vmcnt(0)" ::: "memory");
;     __syncthreads();
;     if (tid0 == 0) {
;         unsigned* bar = b.bar;
;         __builtin_amdgcn_s_waitcnt(0);
;         unsigned nloc = b.st[0], nx = b.st[1];
;         if (nloc == 0u) { xcd_barrier_complete(bar, b.x, nloc, nx); b.st[0] = nloc; b.st[1] = nx; }
;         const unsigned old = xb_add(&bar[XB_XSUB(b.x)], 1u);
; __global__ void __launch_bounds__(512) fwd_kernel(Params p) {
;     ...
;         if (flags & 2) { if (s == 0) grid.sync(); else { const __attribute__((address_space(4))) unsigned char* kb = (const __attribute__((address_space(4))) unsigned char*)__builtin_amdgcn_kernarg_segment_ptr(); asm volatile("" : "+s"(kb));
;             XcdBarrier xb; xb.bar = (unsigned*)(*(unsigned char* const __attribute__((address_space(4)))*)(kb + 192) + WS_BAR); xb.x = xb_xcc_id(); xb.st = (volatile LAS unsigned*)(lds + LDS_BARST); xcd_barrier(xb, tid); } }
.LBB0_1307:
	s_cmp_lg_u32 s46, -1
	s_cbranch_scc0 .LBB0_1319
	s_mov_b64 s[2:3], s[44:45]
	s_getreg_b32 s6, hwreg(HW_REG_XCC_ID, 0, 4)
	s_waitcnt vmcnt(0)
	v_cmp_eq_u32_e32 vcc, 0, v194
	s_waitcnt vmcnt(0) lgkmcnt(0)
	s_barrier
	s_and_saveexec_b64 s[0:1], vcc
	s_cbranch_execz .LBB0_1416
	s_load_dwordx2 s[4:5], s[2:3], 0xc0
	v_readlane_b32 s2, v254, 7
	s_waitcnt vmcnt(0) expcnt(0) lgkmcnt(0)
	s_and_b32 s33, s6, 15
	v_mov_b32_e32 v1, s2
	ds_read_b32 v3, v1
	v_readlane_b32 s2, v254, 8
	s_waitcnt lgkmcnt(0)
	v_cmp_ne_u32_e32 vcc, 0, v3
	v_mov_b32_e32 v1, s2
	ds_read_b32 v2, v1
	s_cbranch_vccnz .LBB0_1325
	s_add_u32 s2, s4, 0x10200
	s_addc_u32 s3, s5, 0
	s_add_u32 s6, s4, 0x10400
	s_addc_u32 s7, s5, 0
	s_add_u32 s8, s4, 0x10500
	s_addc_u32 s9, s5, 0
	s_add_u32 s10, s4, 0x10600
	s_addc_u32 s11, s5, 0
	s_add_u32 s12, s4, 0x10700
	s_addc_u32 s13, s5, 0
	s_add_u32 s14, s4, 0x10800
	s_addc_u32 s15, s5, 0
	s_add_u32 s16, s4, 0x10900
	s_addc_u32 s17, s5, 0
	s_add_u32 s18, s4, 0x10a00
	s_addc_u32 s19, s5, 0
	s_add_u32 s20, s4, 0x10b00
	s_addc_u32 s21, s5, 0
	s_add_u32 s22, s4, 0x10c00
	s_addc_u32 s23, s5, 0
	s_add_u32 s24, s4, 0x10d00
	s_addc_u32 s25, s5, 0
	s_add_u32 s26, s4, 0x10e00
	s_addc_u32 s27, s5, 0
	s_add_u32 s28, s4, 0x10f00
	s_addc_u32 s29, s5, 0
	s_add_u32 s30, s4, 0x11000
	s_addc_u32 s31, s5, 0
	s_add_u32 s36, s4, 0x11100
	s_addc_u32 s37, s5, 0
	s_add_u32 s42, s4, 0x11200
	s_addc_u32 s43, s5, 0
	s_add_u32 s44, s4, 0x11300
	s_mov_b32 s52, s46
	s_addc_u32 s45, s5, 0
	s_mov_b32 s35, 1
	s_branch .LBB0_1312
